# EpiRes GEMM epilogues: serialized per-piece load-wait-store ladder replaced by pipelined loads (latent tiles) and preloaded gates + streamed atomics (ctx tile); on top of rescheduled attention loop
# speedup vs baseline: 1.0033x; 1.0033x over previous
.LBB0_593:
	v_mov_b32_e32 v144, v150
	v_lshl_add_u32 v154, s40, 8, v151
	v_mov_b32_e32 v132, s53
	v_cmp_gt_i32_e32 vcc, s66, v154
	v_add_u32_e32 v130, 0xffffff00, v154
	v_ashrrev_i32_e32 v131, 31, v154
	v_mov_b32_e32 v133, s45
	v_cndmask_b32_e32 v131, 0, v131, vcc
	v_cndmask_b32_e32 v130, v130, v154, vcc
	v_cndmask_b32_e32 v133, v132, v133, vcc
	v_mov_b32_e32 v132, s52
	v_mov_b32_e32 v145, s44
	v_cndmask_b32_e32 v132, v132, v145, vcc
	v_lshlrev_b64 v[130:131], 12, v[130:131]
	s_lshl_b32 s19, s41, 8
	v_lshl_add_u64 v[130:131], v[132:133], 0, v[130:131]
	v_mov_b32_e32 v132, s49
	v_mov_b32_e32 v133, s57
	s_or_b32 s19, s19, s64
	v_cndmask_b32_e32 v133, v132, v133, vcc
	v_mov_b32_e32 v132, s48
	v_mov_b32_e32 v145, s56
	v_lshl_add_u32 v144, v144, 3, s19
	v_cndmask_b32_e32 v132, v132, v145, vcc
	v_ashrrev_i32_e32 v145, 31, v144
	v_lshlrev_b64 v[144:145], 2, v[144:145]
	v_lshl_add_u64 v[148:149], v[132:133], 0, v[144:145]
	v_lshl_add_u64 v[146:147], v[130:131], 0, v[144:145]
	global_load_dwordx4 v[130:133], v[148:149], off
	s_cmp_lg_u32 s40, 0
	s_cselect_b64 s[24:25], -1, 0
	s_and_b64 vcc, exec, s[24:25]
	s_movk_i32 s88, 0xf0
	s_cbranch_vccz .Lres1_atomic
	global_load_dwordx4 v[156:159], v[148:149], off offset:16
	global_load_dwordx4 v[160:163], v[148:149], off offset:512
	global_load_dwordx4 v[164:167], v[148:149], off offset:528
	global_load_dwordx4 v[168:171], v[146:147], off
	global_load_dwordx4 v[172:175], v[146:147], off offset:16
	global_load_dwordx4 v[176:179], v[146:147], off offset:512
	global_load_dwordx4 v[180:183], v[146:147], off offset:528
	s_mov_b32 s24, 0x10000
	s_mov_b32 s25, 0
	v_lshl_add_u64 v[218:219], v[146:147], 0, s[24:25]
	global_load_dwordx4 v[184:187], v[218:219], off
	global_load_dwordx4 v[204:207], v[218:219], off offset:16
	global_load_dwordx4 v[208:211], v[218:219], off offset:512
	global_load_dwordx4 v[212:215], v[218:219], off offset:528
	s_waitcnt vmcnt(4)
	v_pk_fma_f32 v[170:171], v[128:129], v[132:133], v[170:171]
	v_pk_fma_f32 v[168:169], v[126:127], v[130:131], v[168:169]
	v_pk_fma_f32 v[174:175], v[124:125], v[158:159], v[174:175]
	v_pk_fma_f32 v[172:173], v[122:123], v[156:157], v[172:173]
	v_pk_fma_f32 v[178:179], v[120:121], v[162:163], v[178:179]
	v_pk_fma_f32 v[176:177], v[118:119], v[160:161], v[176:177]
	v_pk_fma_f32 v[182:183], v[116:117], v[166:167], v[182:183]
	v_pk_fma_f32 v[180:181], v[114:115], v[164:165], v[180:181]
	global_store_dwordx4 v[146:147], v[168:171], off
	global_store_dwordx4 v[146:147], v[172:175], off offset:16
	global_store_dwordx4 v[146:147], v[176:179], off offset:512
	global_store_dwordx4 v[146:147], v[180:183], off offset:528
	s_mov_b32 s24, 0x20000
	s_nop 1
	v_lshl_add_u64 v[216:217], v[146:147], 0, s[24:25]
	global_load_dwordx4 v[168:171], v[216:217], off
	global_load_dwordx4 v[172:175], v[216:217], off offset:16
	global_load_dwordx4 v[176:179], v[216:217], off offset:512
	global_load_dwordx4 v[180:183], v[216:217], off offset:528
	s_waitcnt vmcnt(8)
	v_pk_fma_f32 v[186:187], v[112:113], v[132:133], v[186:187]
	v_pk_fma_f32 v[184:185], v[110:111], v[130:131], v[184:185]
	v_pk_fma_f32 v[206:207], v[108:109], v[158:159], v[206:207]
	v_pk_fma_f32 v[204:205], v[106:107], v[156:157], v[204:205]
	v_pk_fma_f32 v[210:211], v[104:105], v[162:163], v[210:211]
	v_pk_fma_f32 v[208:209], v[102:103], v[160:161], v[208:209]
	v_pk_fma_f32 v[214:215], v[100:101], v[166:167], v[214:215]
	v_pk_fma_f32 v[212:213], v[98:99], v[164:165], v[212:213]
	global_store_dwordx4 v[218:219], v[184:187], off
	global_store_dwordx4 v[218:219], v[204:207], off offset:16
	global_store_dwordx4 v[218:219], v[208:211], off offset:512
	global_store_dwordx4 v[218:219], v[212:215], off offset:528
	s_mov_b32 s24, 0x30000
	s_nop 1
	v_lshl_add_u64 v[218:219], v[146:147], 0, s[24:25]
	global_load_dwordx4 v[184:187], v[218:219], off
	global_load_dwordx4 v[204:207], v[218:219], off offset:16
	global_load_dwordx4 v[208:211], v[218:219], off offset:512
	global_load_dwordx4 v[212:215], v[218:219], off offset:528
	s_waitcnt vmcnt(8)
	v_pk_fma_f32 v[170:171], v[96:97], v[132:133], v[170:171]
	v_pk_fma_f32 v[168:169], v[94:95], v[130:131], v[168:169]
	v_pk_fma_f32 v[174:175], v[92:93], v[158:159], v[174:175]
	v_pk_fma_f32 v[172:173], v[90:91], v[156:157], v[172:173]
	v_pk_fma_f32 v[178:179], v[88:89], v[162:163], v[178:179]
	v_pk_fma_f32 v[176:177], v[86:87], v[160:161], v[176:177]
	v_pk_fma_f32 v[182:183], v[84:85], v[166:167], v[182:183]
	v_pk_fma_f32 v[180:181], v[82:83], v[164:165], v[180:181]
	global_store_dwordx4 v[216:217], v[168:171], off
	global_store_dwordx4 v[216:217], v[172:175], off offset:16
	global_store_dwordx4 v[216:217], v[176:179], off offset:512
	global_store_dwordx4 v[216:217], v[180:183], off offset:528
	s_mov_b32 s24, 0x80000
	s_nop 1
	v_lshl_add_u64 v[216:217], v[146:147], 0, s[24:25]
	global_load_dwordx4 v[168:171], v[216:217], off
	global_load_dwordx4 v[172:175], v[216:217], off offset:16
	global_load_dwordx4 v[176:179], v[216:217], off offset:512
	global_load_dwordx4 v[180:183], v[216:217], off offset:528
	s_waitcnt vmcnt(8)
	v_pk_fma_f32 v[186:187], v[80:81], v[132:133], v[186:187]
	v_pk_fma_f32 v[184:185], v[78:79], v[130:131], v[184:185]
	v_pk_fma_f32 v[206:207], v[76:77], v[158:159], v[206:207]
	v_pk_fma_f32 v[204:205], v[74:75], v[156:157], v[204:205]
	v_pk_fma_f32 v[210:211], v[72:73], v[162:163], v[210:211]
	v_pk_fma_f32 v[208:209], v[70:71], v[160:161], v[208:209]
	v_pk_fma_f32 v[214:215], v[68:69], v[166:167], v[214:215]
	v_pk_fma_f32 v[212:213], v[66:67], v[164:165], v[212:213]
	global_store_dwordx4 v[218:219], v[184:187], off
	global_store_dwordx4 v[218:219], v[204:207], off offset:16
	global_store_dwordx4 v[218:219], v[208:211], off offset:512
	global_store_dwordx4 v[218:219], v[212:215], off offset:528
	s_mov_b32 s24, 0x90000
	s_nop 1
	v_lshl_add_u64 v[218:219], v[146:147], 0, s[24:25]
	global_load_dwordx4 v[184:187], v[218:219], off
	global_load_dwordx4 v[204:207], v[218:219], off offset:16
	global_load_dwordx4 v[208:211], v[218:219], off offset:512
	global_load_dwordx4 v[212:215], v[218:219], off offset:528
	s_waitcnt vmcnt(8)
	v_pk_fma_f32 v[170:171], v[64:65], v[132:133], v[170:171]
	v_pk_fma_f32 v[168:169], v[62:63], v[130:131], v[168:169]
	v_pk_fma_f32 v[174:175], v[60:61], v[158:159], v[174:175]
	v_pk_fma_f32 v[172:173], v[58:59], v[156:157], v[172:173]
	v_pk_fma_f32 v[178:179], v[56:57], v[162:163], v[178:179]
	v_pk_fma_f32 v[176:177], v[54:55], v[160:161], v[176:177]
	v_pk_fma_f32 v[182:183], v[52:53], v[166:167], v[182:183]
	v_pk_fma_f32 v[180:181], v[50:51], v[164:165], v[180:181]
	global_store_dwordx4 v[216:217], v[168:171], off
	global_store_dwordx4 v[216:217], v[172:175], off offset:16
	global_store_dwordx4 v[216:217], v[176:179], off offset:512
	global_store_dwordx4 v[216:217], v[180:183], off offset:528
	s_mov_b32 s24, 0xa0000
	s_nop 1
	v_lshl_add_u64 v[216:217], v[146:147], 0, s[24:25]
	global_load_dwordx4 v[168:171], v[216:217], off
	global_load_dwordx4 v[172:175], v[216:217], off offset:16
	global_load_dwordx4 v[176:179], v[216:217], off offset:512
	global_load_dwordx4 v[180:183], v[216:217], off offset:528
	s_waitcnt vmcnt(8)
	v_pk_fma_f32 v[186:187], v[48:49], v[132:133], v[186:187]
	v_pk_fma_f32 v[184:185], v[46:47], v[130:131], v[184:185]
	v_pk_fma_f32 v[206:207], v[44:45], v[158:159], v[206:207]
	v_pk_fma_f32 v[204:205], v[42:43], v[156:157], v[204:205]
	v_pk_fma_f32 v[210:211], v[40:41], v[162:163], v[210:211]
	v_pk_fma_f32 v[208:209], v[38:39], v[160:161], v[208:209]
	v_pk_fma_f32 v[214:215], v[36:37], v[166:167], v[214:215]
	v_pk_fma_f32 v[212:213], v[34:35], v[164:165], v[212:213]
	global_store_dwordx4 v[218:219], v[184:187], off
	global_store_dwordx4 v[218:219], v[204:207], off offset:16
	global_store_dwordx4 v[218:219], v[208:211], off offset:512
	global_store_dwordx4 v[218:219], v[212:215], off offset:528
	s_mov_b32 s24, 0xb0000
	s_nop 1
	v_lshl_add_u64 v[218:219], v[146:147], 0, s[24:25]
	global_load_dwordx4 v[184:187], v[218:219], off
	global_load_dwordx4 v[204:207], v[218:219], off offset:16
	global_load_dwordx4 v[208:211], v[218:219], off offset:512
	global_load_dwordx4 v[212:215], v[218:219], off offset:528
	s_waitcnt vmcnt(8)
	v_pk_fma_f32 v[170:171], v[32:33], v[132:133], v[170:171]
	v_pk_fma_f32 v[168:169], v[30:31], v[130:131], v[168:169]
	v_pk_fma_f32 v[174:175], v[28:29], v[158:159], v[174:175]
	v_pk_fma_f32 v[172:173], v[26:27], v[156:157], v[172:173]
	v_pk_fma_f32 v[178:179], v[24:25], v[162:163], v[178:179]
	v_pk_fma_f32 v[176:177], v[22:23], v[160:161], v[176:177]
	v_pk_fma_f32 v[182:183], v[20:21], v[166:167], v[182:183]
	v_pk_fma_f32 v[180:181], v[18:19], v[164:165], v[180:181]
	global_store_dwordx4 v[216:217], v[168:171], off
	global_store_dwordx4 v[216:217], v[172:175], off offset:16
	global_store_dwordx4 v[216:217], v[176:179], off offset:512
	global_store_dwordx4 v[216:217], v[180:183], off offset:528
	s_waitcnt vmcnt(4)
	v_pk_fma_f32 v[186:187], v[16:17], v[132:133], v[186:187]
	v_pk_fma_f32 v[184:185], v[14:15], v[130:131], v[184:185]
	v_pk_fma_f32 v[206:207], v[12:13], v[158:159], v[206:207]
	v_pk_fma_f32 v[204:205], v[10:11], v[156:157], v[204:205]
	v_pk_fma_f32 v[210:211], v[8:9], v[162:163], v[210:211]
	v_pk_fma_f32 v[208:209], v[6:7], v[160:161], v[208:209]
	v_pk_fma_f32 v[214:215], v[4:5], v[166:167], v[214:215]
	v_pk_fma_f32 v[212:213], v[2:3], v[164:165], v[212:213]
	global_store_dwordx4 v[218:219], v[184:187], off
	global_store_dwordx4 v[218:219], v[204:207], off offset:16
	global_store_dwordx4 v[218:219], v[208:211], off offset:512
	global_store_dwordx4 v[218:219], v[212:215], off offset:528
	s_movk_i32 s87, 0x80
	s_mov_b32 s75, s73
	s_mov_b64 s[40:41], 0
	s_movk_i32 s19, 0x70
	s_branch .LBB0_689
.Lres1_atomic:
	global_load_dwordx4 v[156:159], v[148:149], off offset:16
	global_load_dwordx4 v[160:163], v[148:149], off offset:512
	global_load_dwordx4 v[164:167], v[148:149], off offset:528
	s_mov_b32 s25, 0
	s_waitcnt vmcnt(0)
	v_pk_mul_f32 v[126:127], v[126:127], v[130:131]
	v_pk_mul_f32 v[128:129], v[128:129], v[132:133]
	global_atomic_add_f32 v[146:147], v126, off
	global_atomic_add_f32 v[146:147], v127, off offset:4
	global_atomic_add_f32 v[146:147], v128, off offset:8
	global_atomic_add_f32 v[146:147], v129, off offset:12
	v_pk_mul_f32 v[122:123], v[122:123], v[156:157]
	v_pk_mul_f32 v[124:125], v[124:125], v[158:159]
	global_atomic_add_f32 v[146:147], v122, off offset:16
	global_atomic_add_f32 v[146:147], v123, off offset:20
	global_atomic_add_f32 v[146:147], v124, off offset:24
	global_atomic_add_f32 v[146:147], v125, off offset:28
	v_pk_mul_f32 v[118:119], v[118:119], v[160:161]
	v_pk_mul_f32 v[120:121], v[120:121], v[162:163]
	global_atomic_add_f32 v[146:147], v118, off offset:512
	global_atomic_add_f32 v[146:147], v119, off offset:516
	global_atomic_add_f32 v[146:147], v120, off offset:520
	global_atomic_add_f32 v[146:147], v121, off offset:524
	v_pk_mul_f32 v[114:115], v[114:115], v[164:165]
	v_pk_mul_f32 v[116:117], v[116:117], v[166:167]
	global_atomic_add_f32 v[146:147], v114, off offset:528
	global_atomic_add_f32 v[146:147], v115, off offset:532
	global_atomic_add_f32 v[146:147], v116, off offset:536
	global_atomic_add_f32 v[146:147], v117, off offset:540
	s_mov_b32 s24, 0x10000
	v_lshl_add_u64 v[218:219], v[146:147], 0, s[24:25]
	v_pk_mul_f32 v[110:111], v[110:111], v[130:131]
	v_pk_mul_f32 v[112:113], v[112:113], v[132:133]
	global_atomic_add_f32 v[218:219], v110, off
	global_atomic_add_f32 v[218:219], v111, off offset:4
	global_atomic_add_f32 v[218:219], v112, off offset:8
	global_atomic_add_f32 v[218:219], v113, off offset:12
	v_pk_mul_f32 v[106:107], v[106:107], v[156:157]
	v_pk_mul_f32 v[108:109], v[108:109], v[158:159]
	global_atomic_add_f32 v[218:219], v106, off offset:16
	global_atomic_add_f32 v[218:219], v107, off offset:20
	global_atomic_add_f32 v[218:219], v108, off offset:24
	global_atomic_add_f32 v[218:219], v109, off offset:28
	v_pk_mul_f32 v[102:103], v[102:103], v[160:161]
	v_pk_mul_f32 v[104:105], v[104:105], v[162:163]
	global_atomic_add_f32 v[218:219], v102, off offset:512
	global_atomic_add_f32 v[218:219], v103, off offset:516
	global_atomic_add_f32 v[218:219], v104, off offset:520
	global_atomic_add_f32 v[218:219], v105, off offset:524
	v_pk_mul_f32 v[98:99], v[98:99], v[164:165]
	v_pk_mul_f32 v[100:101], v[100:101], v[166:167]
	global_atomic_add_f32 v[218:219], v98, off offset:528
	global_atomic_add_f32 v[218:219], v99, off offset:532
	global_atomic_add_f32 v[218:219], v100, off offset:536
	global_atomic_add_f32 v[218:219], v101, off offset:540
	s_mov_b32 s24, 0x20000
	v_lshl_add_u64 v[216:217], v[146:147], 0, s[24:25]
	v_pk_mul_f32 v[94:95], v[94:95], v[130:131]
	v_pk_mul_f32 v[96:97], v[96:97], v[132:133]
	global_atomic_add_f32 v[216:217], v94, off
	global_atomic_add_f32 v[216:217], v95, off offset:4
	global_atomic_add_f32 v[216:217], v96, off offset:8
	global_atomic_add_f32 v[216:217], v97, off offset:12
	v_pk_mul_f32 v[90:91], v[90:91], v[156:157]
	v_pk_mul_f32 v[92:93], v[92:93], v[158:159]
	global_atomic_add_f32 v[216:217], v90, off offset:16
	global_atomic_add_f32 v[216:217], v91, off offset:20
	global_atomic_add_f32 v[216:217], v92, off offset:24
	global_atomic_add_f32 v[216:217], v93, off offset:28
	v_pk_mul_f32 v[86:87], v[86:87], v[160:161]
	v_pk_mul_f32 v[88:89], v[88:89], v[162:163]
	global_atomic_add_f32 v[216:217], v86, off offset:512
	global_atomic_add_f32 v[216:217], v87, off offset:516
	global_atomic_add_f32 v[216:217], v88, off offset:520
	global_atomic_add_f32 v[216:217], v89, off offset:524
	v_pk_mul_f32 v[82:83], v[82:83], v[164:165]
	v_pk_mul_f32 v[84:85], v[84:85], v[166:167]
	global_atomic_add_f32 v[216:217], v82, off offset:528
	global_atomic_add_f32 v[216:217], v83, off offset:532
	global_atomic_add_f32 v[216:217], v84, off offset:536
	global_atomic_add_f32 v[216:217], v85, off offset:540
	s_mov_b32 s24, 0x30000
	v_lshl_add_u64 v[218:219], v[146:147], 0, s[24:25]
	v_pk_mul_f32 v[78:79], v[78:79], v[130:131]
	v_pk_mul_f32 v[80:81], v[80:81], v[132:133]
	global_atomic_add_f32 v[218:219], v78, off
	global_atomic_add_f32 v[218:219], v79, off offset:4
	global_atomic_add_f32 v[218:219], v80, off offset:8
	global_atomic_add_f32 v[218:219], v81, off offset:12
	v_pk_mul_f32 v[74:75], v[74:75], v[156:157]
	v_pk_mul_f32 v[76:77], v[76:77], v[158:159]
	global_atomic_add_f32 v[218:219], v74, off offset:16
	global_atomic_add_f32 v[218:219], v75, off offset:20
	global_atomic_add_f32 v[218:219], v76, off offset:24
	global_atomic_add_f32 v[218:219], v77, off offset:28
	v_pk_mul_f32 v[70:71], v[70:71], v[160:161]
	v_pk_mul_f32 v[72:73], v[72:73], v[162:163]
	global_atomic_add_f32 v[218:219], v70, off offset:512
	global_atomic_add_f32 v[218:219], v71, off offset:516
	global_atomic_add_f32 v[218:219], v72, off offset:520
	global_atomic_add_f32 v[218:219], v73, off offset:524
	v_pk_mul_f32 v[66:67], v[66:67], v[164:165]
	v_pk_mul_f32 v[68:69], v[68:69], v[166:167]
	global_atomic_add_f32 v[218:219], v66, off offset:528
	global_atomic_add_f32 v[218:219], v67, off offset:532
	global_atomic_add_f32 v[218:219], v68, off offset:536
	global_atomic_add_f32 v[218:219], v69, off offset:540
	s_mov_b32 s24, 0x80000
	v_lshl_add_u64 v[216:217], v[146:147], 0, s[24:25]
	v_pk_mul_f32 v[62:63], v[62:63], v[130:131]
	v_pk_mul_f32 v[64:65], v[64:65], v[132:133]
	global_atomic_add_f32 v[216:217], v62, off
	global_atomic_add_f32 v[216:217], v63, off offset:4
	global_atomic_add_f32 v[216:217], v64, off offset:8
	global_atomic_add_f32 v[216:217], v65, off offset:12
	v_pk_mul_f32 v[58:59], v[58:59], v[156:157]
	v_pk_mul_f32 v[60:61], v[60:61], v[158:159]
	global_atomic_add_f32 v[216:217], v58, off offset:16
	global_atomic_add_f32 v[216:217], v59, off offset:20
	global_atomic_add_f32 v[216:217], v60, off offset:24
	global_atomic_add_f32 v[216:217], v61, off offset:28
	v_pk_mul_f32 v[54:55], v[54:55], v[160:161]
	v_pk_mul_f32 v[56:57], v[56:57], v[162:163]
	global_atomic_add_f32 v[216:217], v54, off offset:512
	global_atomic_add_f32 v[216:217], v55, off offset:516
	global_atomic_add_f32 v[216:217], v56, off offset:520
	global_atomic_add_f32 v[216:217], v57, off offset:524
	v_pk_mul_f32 v[50:51], v[50:51], v[164:165]
	v_pk_mul_f32 v[52:53], v[52:53], v[166:167]
	global_atomic_add_f32 v[216:217], v50, off offset:528
	global_atomic_add_f32 v[216:217], v51, off offset:532
	global_atomic_add_f32 v[216:217], v52, off offset:536
	global_atomic_add_f32 v[216:217], v53, off offset:540
	s_mov_b32 s24, 0x90000
	v_lshl_add_u64 v[218:219], v[146:147], 0, s[24:25]
	v_pk_mul_f32 v[46:47], v[46:47], v[130:131]
	v_pk_mul_f32 v[48:49], v[48:49], v[132:133]
	global_atomic_add_f32 v[218:219], v46, off
	global_atomic_add_f32 v[218:219], v47, off offset:4
	global_atomic_add_f32 v[218:219], v48, off offset:8
	global_atomic_add_f32 v[218:219], v49, off offset:12
	v_pk_mul_f32 v[42:43], v[42:43], v[156:157]
	v_pk_mul_f32 v[44:45], v[44:45], v[158:159]
	global_atomic_add_f32 v[218:219], v42, off offset:16
	global_atomic_add_f32 v[218:219], v43, off offset:20
	global_atomic_add_f32 v[218:219], v44, off offset:24
	global_atomic_add_f32 v[218:219], v45, off offset:28
	v_pk_mul_f32 v[38:39], v[38:39], v[160:161]
	v_pk_mul_f32 v[40:41], v[40:41], v[162:163]
	global_atomic_add_f32 v[218:219], v38, off offset:512
	global_atomic_add_f32 v[218:219], v39, off offset:516
	global_atomic_add_f32 v[218:219], v40, off offset:520
	global_atomic_add_f32 v[218:219], v41, off offset:524
	v_pk_mul_f32 v[34:35], v[34:35], v[164:165]
	v_pk_mul_f32 v[36:37], v[36:37], v[166:167]
	global_atomic_add_f32 v[218:219], v34, off offset:528
	global_atomic_add_f32 v[218:219], v35, off offset:532
	global_atomic_add_f32 v[218:219], v36, off offset:536
	global_atomic_add_f32 v[218:219], v37, off offset:540
	s_mov_b32 s24, 0xa0000
	v_lshl_add_u64 v[216:217], v[146:147], 0, s[24:25]
	v_pk_mul_f32 v[30:31], v[30:31], v[130:131]
	v_pk_mul_f32 v[32:33], v[32:33], v[132:133]
	global_atomic_add_f32 v[216:217], v30, off
	global_atomic_add_f32 v[216:217], v31, off offset:4
	global_atomic_add_f32 v[216:217], v32, off offset:8
	global_atomic_add_f32 v[216:217], v33, off offset:12
	v_pk_mul_f32 v[26:27], v[26:27], v[156:157]
	v_pk_mul_f32 v[28:29], v[28:29], v[158:159]
	global_atomic_add_f32 v[216:217], v26, off offset:16
	global_atomic_add_f32 v[216:217], v27, off offset:20
	global_atomic_add_f32 v[216:217], v28, off offset:24
	global_atomic_add_f32 v[216:217], v29, off offset:28
	v_pk_mul_f32 v[22:23], v[22:23], v[160:161]
	v_pk_mul_f32 v[24:25], v[24:25], v[162:163]
	global_atomic_add_f32 v[216:217], v22, off offset:512
	global_atomic_add_f32 v[216:217], v23, off offset:516
	global_atomic_add_f32 v[216:217], v24, off offset:520
	global_atomic_add_f32 v[216:217], v25, off offset:524
	v_pk_mul_f32 v[18:19], v[18:19], v[164:165]
	v_pk_mul_f32 v[20:21], v[20:21], v[166:167]
	global_atomic_add_f32 v[216:217], v18, off offset:528
	global_atomic_add_f32 v[216:217], v19, off offset:532
	global_atomic_add_f32 v[216:217], v20, off offset:536
	global_atomic_add_f32 v[216:217], v21, off offset:540
	s_mov_b32 s24, 0xb0000
	v_lshl_add_u64 v[218:219], v[146:147], 0, s[24:25]
	v_pk_mul_f32 v[14:15], v[14:15], v[130:131]
	v_pk_mul_f32 v[16:17], v[16:17], v[132:133]
	global_atomic_add_f32 v[218:219], v14, off
	global_atomic_add_f32 v[218:219], v15, off offset:4
	global_atomic_add_f32 v[218:219], v16, off offset:8
	global_atomic_add_f32 v[218:219], v17, off offset:12
	v_pk_mul_f32 v[10:11], v[10:11], v[156:157]
	v_pk_mul_f32 v[12:13], v[12:13], v[158:159]
	global_atomic_add_f32 v[218:219], v10, off offset:16
	global_atomic_add_f32 v[218:219], v11, off offset:20
	global_atomic_add_f32 v[218:219], v12, off offset:24
	global_atomic_add_f32 v[218:219], v13, off offset:28
	v_pk_mul_f32 v[6:7], v[6:7], v[160:161]
	v_pk_mul_f32 v[8:9], v[8:9], v[162:163]
	global_atomic_add_f32 v[218:219], v6, off offset:512
	global_atomic_add_f32 v[218:219], v7, off offset:516
	global_atomic_add_f32 v[218:219], v8, off offset:520
	global_atomic_add_f32 v[218:219], v9, off offset:524
	v_pk_mul_f32 v[2:3], v[2:3], v[164:165]
	v_pk_mul_f32 v[4:5], v[4:5], v[166:167]
	global_atomic_add_f32 v[218:219], v2, off offset:528
	global_atomic_add_f32 v[218:219], v3, off offset:532
	global_atomic_add_f32 v[218:219], v4, off offset:536
	global_atomic_add_f32 v[218:219], v5, off offset:540
	s_movk_i32 s87, 0x80
	s_mov_b32 s75, s73
	s_mov_b64 s[40:41], exec
	s_movk_i32 s19, 0x70
	s_branch .LBB0_689
	global_load_dwordx4 v[156:159], v[146:147], off
	s_waitcnt vmcnt(0)
	v_pk_fma_f32 v[158:159], v[128:129], v[132:133], v[158:159]
	v_pk_fma_f32 v[156:157], v[126:127], v[130:131], v[156:157]
	global_store_dwordx4 v[146:147], v[156:159], off
	s_movk_i32 s87, 0x80
	s_mov_b32 s75, s73
	s_cbranch_execnz .LBB0_596

.LBB0_1769:
	v_mov_b32_e32 v144, v150
	v_lshl_add_u32 v154, s40, 8, v151
	v_mov_b32_e32 v132, s53
	v_cmp_gt_i32_e32 vcc, s66, v154
	v_add_u32_e32 v130, 0xffffff00, v154
	v_ashrrev_i32_e32 v131, 31, v154
	v_mov_b32_e32 v133, s43
	v_cndmask_b32_e32 v131, 0, v131, vcc
	v_cndmask_b32_e32 v130, v130, v154, vcc
	v_cndmask_b32_e32 v133, v132, v133, vcc
	v_mov_b32_e32 v132, s52
	v_mov_b32_e32 v145, s42
	v_cndmask_b32_e32 v132, v132, v145, vcc
	v_lshlrev_b64 v[130:131], 12, v[130:131]
	s_lshl_b32 s19, s41, 8
	v_lshl_add_u64 v[130:131], v[132:133], 0, v[130:131]
	v_mov_b32_e32 v132, s45
	v_mov_b32_e32 v133, s49
	s_or_b32 s19, s19, s58
	v_cndmask_b32_e32 v133, v132, v133, vcc
	v_mov_b32_e32 v132, s44
	v_mov_b32_e32 v145, s48
	v_lshl_add_u32 v144, v144, 3, s19
	v_cndmask_b32_e32 v132, v132, v145, vcc
	v_ashrrev_i32_e32 v145, 31, v144
	v_lshlrev_b64 v[144:145], 2, v[144:145]
	v_lshl_add_u64 v[148:149], v[132:133], 0, v[144:145]
	v_lshl_add_u64 v[146:147], v[130:131], 0, v[144:145]
	global_load_dwordx4 v[130:133], v[148:149], off
	s_cmp_lg_u32 s40, 0
	s_cselect_b64 s[24:25], -1, 0
	s_and_b64 vcc, exec, s[24:25]
	s_cbranch_vccz .Lres2_atomic
	global_load_dwordx4 v[156:159], v[148:149], off offset:16
	global_load_dwordx4 v[160:163], v[148:149], off offset:512
	global_load_dwordx4 v[164:167], v[148:149], off offset:528
	global_load_dwordx4 v[168:171], v[146:147], off
	global_load_dwordx4 v[172:175], v[146:147], off offset:16
	global_load_dwordx4 v[176:179], v[146:147], off offset:512
	global_load_dwordx4 v[180:183], v[146:147], off offset:528
	s_mov_b32 s24, 0x10000
	s_mov_b32 s25, 0
	v_lshl_add_u64 v[218:219], v[146:147], 0, s[24:25]
	global_load_dwordx4 v[184:187], v[218:219], off
	global_load_dwordx4 v[204:207], v[218:219], off offset:16
	global_load_dwordx4 v[208:211], v[218:219], off offset:512
	global_load_dwordx4 v[212:215], v[218:219], off offset:528
	s_waitcnt vmcnt(4)
	v_pk_fma_f32 v[170:171], v[128:129], v[132:133], v[170:171]
	v_pk_fma_f32 v[168:169], v[126:127], v[130:131], v[168:169]
	v_pk_fma_f32 v[174:175], v[124:125], v[158:159], v[174:175]
	v_pk_fma_f32 v[172:173], v[122:123], v[156:157], v[172:173]
	v_pk_fma_f32 v[178:179], v[120:121], v[162:163], v[178:179]
	v_pk_fma_f32 v[176:177], v[118:119], v[160:161], v[176:177]
	v_pk_fma_f32 v[182:183], v[116:117], v[166:167], v[182:183]
	v_pk_fma_f32 v[180:181], v[114:115], v[164:165], v[180:181]
	global_store_dwordx4 v[146:147], v[168:171], off
	global_store_dwordx4 v[146:147], v[172:175], off offset:16
	global_store_dwordx4 v[146:147], v[176:179], off offset:512
	global_store_dwordx4 v[146:147], v[180:183], off offset:528
	s_mov_b32 s24, 0x20000
	s_nop 1
	v_lshl_add_u64 v[216:217], v[146:147], 0, s[24:25]
	global_load_dwordx4 v[168:171], v[216:217], off
	global_load_dwordx4 v[172:175], v[216:217], off offset:16
	global_load_dwordx4 v[176:179], v[216:217], off offset:512
	global_load_dwordx4 v[180:183], v[216:217], off offset:528
	s_waitcnt vmcnt(8)
	v_pk_fma_f32 v[186:187], v[112:113], v[132:133], v[186:187]
	v_pk_fma_f32 v[184:185], v[110:111], v[130:131], v[184:185]
	v_pk_fma_f32 v[206:207], v[108:109], v[158:159], v[206:207]
	v_pk_fma_f32 v[204:205], v[106:107], v[156:157], v[204:205]
	v_pk_fma_f32 v[210:211], v[104:105], v[162:163], v[210:211]
	v_pk_fma_f32 v[208:209], v[102:103], v[160:161], v[208:209]
	v_pk_fma_f32 v[214:215], v[100:101], v[166:167], v[214:215]
	v_pk_fma_f32 v[212:213], v[98:99], v[164:165], v[212:213]
	global_store_dwordx4 v[218:219], v[184:187], off
	global_store_dwordx4 v[218:219], v[204:207], off offset:16
	global_store_dwordx4 v[218:219], v[208:211], off offset:512
	global_store_dwordx4 v[218:219], v[212:215], off offset:528
	s_mov_b32 s24, 0x30000
	s_nop 1
	v_lshl_add_u64 v[218:219], v[146:147], 0, s[24:25]
	global_load_dwordx4 v[184:187], v[218:219], off
	global_load_dwordx4 v[204:207], v[218:219], off offset:16
	global_load_dwordx4 v[208:211], v[218:219], off offset:512
	global_load_dwordx4 v[212:215], v[218:219], off offset:528
	s_waitcnt vmcnt(8)
	v_pk_fma_f32 v[170:171], v[96:97], v[132:133], v[170:171]
	v_pk_fma_f32 v[168:169], v[94:95], v[130:131], v[168:169]
	v_pk_fma_f32 v[174:175], v[92:93], v[158:159], v[174:175]
	v_pk_fma_f32 v[172:173], v[90:91], v[156:157], v[172:173]
	v_pk_fma_f32 v[178:179], v[88:89], v[162:163], v[178:179]
	v_pk_fma_f32 v[176:177], v[86:87], v[160:161], v[176:177]
	v_pk_fma_f32 v[182:183], v[84:85], v[166:167], v[182:183]
	v_pk_fma_f32 v[180:181], v[82:83], v[164:165], v[180:181]
	global_store_dwordx4 v[216:217], v[168:171], off
	global_store_dwordx4 v[216:217], v[172:175], off offset:16
	global_store_dwordx4 v[216:217], v[176:179], off offset:512
	global_store_dwordx4 v[216:217], v[180:183], off offset:528
	s_mov_b32 s24, 0x80000
	s_nop 1
	v_lshl_add_u64 v[216:217], v[146:147], 0, s[24:25]
	global_load_dwordx4 v[168:171], v[216:217], off
	global_load_dwordx4 v[172:175], v[216:217], off offset:16
	global_load_dwordx4 v[176:179], v[216:217], off offset:512
	global_load_dwordx4 v[180:183], v[216:217], off offset:528
	s_waitcnt vmcnt(8)
	v_pk_fma_f32 v[186:187], v[80:81], v[132:133], v[186:187]
	v_pk_fma_f32 v[184:185], v[78:79], v[130:131], v[184:185]
	v_pk_fma_f32 v[206:207], v[76:77], v[158:159], v[206:207]
	v_pk_fma_f32 v[204:205], v[74:75], v[156:157], v[204:205]
	v_pk_fma_f32 v[210:211], v[72:73], v[162:163], v[210:211]
	v_pk_fma_f32 v[208:209], v[70:71], v[160:161], v[208:209]
	v_pk_fma_f32 v[214:215], v[68:69], v[166:167], v[214:215]
	v_pk_fma_f32 v[212:213], v[66:67], v[164:165], v[212:213]
	global_store_dwordx4 v[218:219], v[184:187], off
	global_store_dwordx4 v[218:219], v[204:207], off offset:16
	global_store_dwordx4 v[218:219], v[208:211], off offset:512
	global_store_dwordx4 v[218:219], v[212:215], off offset:528
	s_mov_b32 s24, 0x90000
	s_nop 1
	v_lshl_add_u64 v[218:219], v[146:147], 0, s[24:25]
	global_load_dwordx4 v[184:187], v[218:219], off
	global_load_dwordx4 v[204:207], v[218:219], off offset:16
	global_load_dwordx4 v[208:211], v[218:219], off offset:512
	global_load_dwordx4 v[212:215], v[218:219], off offset:528
	s_waitcnt vmcnt(8)
	v_pk_fma_f32 v[170:171], v[64:65], v[132:133], v[170:171]
	v_pk_fma_f32 v[168:169], v[62:63], v[130:131], v[168:169]
	v_pk_fma_f32 v[174:175], v[60:61], v[158:159], v[174:175]
	v_pk_fma_f32 v[172:173], v[58:59], v[156:157], v[172:173]
	v_pk_fma_f32 v[178:179], v[56:57], v[162:163], v[178:179]
	v_pk_fma_f32 v[176:177], v[54:55], v[160:161], v[176:177]
	v_pk_fma_f32 v[182:183], v[52:53], v[166:167], v[182:183]
	v_pk_fma_f32 v[180:181], v[50:51], v[164:165], v[180:181]
	global_store_dwordx4 v[216:217], v[168:171], off
	global_store_dwordx4 v[216:217], v[172:175], off offset:16
	global_store_dwordx4 v[216:217], v[176:179], off offset:512
	global_store_dwordx4 v[216:217], v[180:183], off offset:528
	s_mov_b32 s24, 0xa0000
	s_nop 1
	v_lshl_add_u64 v[216:217], v[146:147], 0, s[24:25]
	global_load_dwordx4 v[168:171], v[216:217], off
	global_load_dwordx4 v[172:175], v[216:217], off offset:16
	global_load_dwordx4 v[176:179], v[216:217], off offset:512
	global_load_dwordx4 v[180:183], v[216:217], off offset:528
	s_waitcnt vmcnt(8)
	v_pk_fma_f32 v[186:187], v[48:49], v[132:133], v[186:187]
	v_pk_fma_f32 v[184:185], v[46:47], v[130:131], v[184:185]
	v_pk_fma_f32 v[206:207], v[44:45], v[158:159], v[206:207]
	v_pk_fma_f32 v[204:205], v[42:43], v[156:157], v[204:205]
	v_pk_fma_f32 v[210:211], v[40:41], v[162:163], v[210:211]
	v_pk_fma_f32 v[208:209], v[38:39], v[160:161], v[208:209]
	v_pk_fma_f32 v[214:215], v[36:37], v[166:167], v[214:215]
	v_pk_fma_f32 v[212:213], v[34:35], v[164:165], v[212:213]
	global_store_dwordx4 v[218:219], v[184:187], off
	global_store_dwordx4 v[218:219], v[204:207], off offset:16
	global_store_dwordx4 v[218:219], v[208:211], off offset:512
	global_store_dwordx4 v[218:219], v[212:215], off offset:528
	s_mov_b32 s24, 0xb0000
	s_nop 1
	v_lshl_add_u64 v[218:219], v[146:147], 0, s[24:25]
	global_load_dwordx4 v[184:187], v[218:219], off
	global_load_dwordx4 v[204:207], v[218:219], off offset:16
	global_load_dwordx4 v[208:211], v[218:219], off offset:512
	global_load_dwordx4 v[212:215], v[218:219], off offset:528
	s_waitcnt vmcnt(8)
	v_pk_fma_f32 v[170:171], v[32:33], v[132:133], v[170:171]
	v_pk_fma_f32 v[168:169], v[30:31], v[130:131], v[168:169]
	v_pk_fma_f32 v[174:175], v[28:29], v[158:159], v[174:175]
	v_pk_fma_f32 v[172:173], v[26:27], v[156:157], v[172:173]
	v_pk_fma_f32 v[178:179], v[24:25], v[162:163], v[178:179]
	v_pk_fma_f32 v[176:177], v[22:23], v[160:161], v[176:177]
	v_pk_fma_f32 v[182:183], v[20:21], v[166:167], v[182:183]
	v_pk_fma_f32 v[180:181], v[18:19], v[164:165], v[180:181]
	global_store_dwordx4 v[216:217], v[168:171], off
	global_store_dwordx4 v[216:217], v[172:175], off offset:16
	global_store_dwordx4 v[216:217], v[176:179], off offset:512
	global_store_dwordx4 v[216:217], v[180:183], off offset:528
	s_waitcnt vmcnt(4)
	v_pk_fma_f32 v[186:187], v[16:17], v[132:133], v[186:187]
	v_pk_fma_f32 v[184:185], v[14:15], v[130:131], v[184:185]
	v_pk_fma_f32 v[206:207], v[12:13], v[158:159], v[206:207]
	v_pk_fma_f32 v[204:205], v[10:11], v[156:157], v[204:205]
	v_pk_fma_f32 v[210:211], v[8:9], v[162:163], v[210:211]
	v_pk_fma_f32 v[208:209], v[6:7], v[160:161], v[208:209]
	v_pk_fma_f32 v[214:215], v[4:5], v[166:167], v[214:215]
	v_pk_fma_f32 v[212:213], v[2:3], v[164:165], v[212:213]
	global_store_dwordx4 v[218:219], v[184:187], off
	global_store_dwordx4 v[218:219], v[204:207], off offset:16
	global_store_dwordx4 v[218:219], v[208:211], off offset:512
	global_store_dwordx4 v[218:219], v[212:215], off offset:528
	s_mov_b64 s[40:41], 0
	s_movk_i32 s19, 0x70
	s_branch .LBB0_1865
.Lres2_atomic:
	global_load_dwordx4 v[156:159], v[148:149], off offset:16
	global_load_dwordx4 v[160:163], v[148:149], off offset:512
	global_load_dwordx4 v[164:167], v[148:149], off offset:528
	s_mov_b32 s25, 0
	s_waitcnt vmcnt(0)
	v_pk_mul_f32 v[126:127], v[126:127], v[130:131]
	v_pk_mul_f32 v[128:129], v[128:129], v[132:133]
	global_atomic_add_f32 v[146:147], v126, off
	global_atomic_add_f32 v[146:147], v127, off offset:4
	global_atomic_add_f32 v[146:147], v128, off offset:8
	global_atomic_add_f32 v[146:147], v129, off offset:12
	v_pk_mul_f32 v[122:123], v[122:123], v[156:157]
	v_pk_mul_f32 v[124:125], v[124:125], v[158:159]
	global_atomic_add_f32 v[146:147], v122, off offset:16
	global_atomic_add_f32 v[146:147], v123, off offset:20
	global_atomic_add_f32 v[146:147], v124, off offset:24
	global_atomic_add_f32 v[146:147], v125, off offset:28
	v_pk_mul_f32 v[118:119], v[118:119], v[160:161]
	v_pk_mul_f32 v[120:121], v[120:121], v[162:163]
	global_atomic_add_f32 v[146:147], v118, off offset:512
	global_atomic_add_f32 v[146:147], v119, off offset:516
	global_atomic_add_f32 v[146:147], v120, off offset:520
	global_atomic_add_f32 v[146:147], v121, off offset:524
	v_pk_mul_f32 v[114:115], v[114:115], v[164:165]
	v_pk_mul_f32 v[116:117], v[116:117], v[166:167]
	global_atomic_add_f32 v[146:147], v114, off offset:528
	global_atomic_add_f32 v[146:147], v115, off offset:532
	global_atomic_add_f32 v[146:147], v116, off offset:536
	global_atomic_add_f32 v[146:147], v117, off offset:540
	s_mov_b32 s24, 0x10000
	v_lshl_add_u64 v[218:219], v[146:147], 0, s[24:25]
	v_pk_mul_f32 v[110:111], v[110:111], v[130:131]
	v_pk_mul_f32 v[112:113], v[112:113], v[132:133]
	global_atomic_add_f32 v[218:219], v110, off
	global_atomic_add_f32 v[218:219], v111, off offset:4
	global_atomic_add_f32 v[218:219], v112, off offset:8
	global_atomic_add_f32 v[218:219], v113, off offset:12
	v_pk_mul_f32 v[106:107], v[106:107], v[156:157]
	v_pk_mul_f32 v[108:109], v[108:109], v[158:159]
	global_atomic_add_f32 v[218:219], v106, off offset:16
	global_atomic_add_f32 v[218:219], v107, off offset:20
	global_atomic_add_f32 v[218:219], v108, off offset:24
	global_atomic_add_f32 v[218:219], v109, off offset:28
	v_pk_mul_f32 v[102:103], v[102:103], v[160:161]
	v_pk_mul_f32 v[104:105], v[104:105], v[162:163]
	global_atomic_add_f32 v[218:219], v102, off offset:512
	global_atomic_add_f32 v[218:219], v103, off offset:516
	global_atomic_add_f32 v[218:219], v104, off offset:520
	global_atomic_add_f32 v[218:219], v105, off offset:524
	v_pk_mul_f32 v[98:99], v[98:99], v[164:165]
	v_pk_mul_f32 v[100:101], v[100:101], v[166:167]
	global_atomic_add_f32 v[218:219], v98, off offset:528
	global_atomic_add_f32 v[218:219], v99, off offset:532
	global_atomic_add_f32 v[218:219], v100, off offset:536
	global_atomic_add_f32 v[218:219], v101, off offset:540
	s_mov_b32 s24, 0x20000
	v_lshl_add_u64 v[216:217], v[146:147], 0, s[24:25]
	v_pk_mul_f32 v[94:95], v[94:95], v[130:131]
	v_pk_mul_f32 v[96:97], v[96:97], v[132:133]
	global_atomic_add_f32 v[216:217], v94, off
	global_atomic_add_f32 v[216:217], v95, off offset:4
	global_atomic_add_f32 v[216:217], v96, off offset:8
	global_atomic_add_f32 v[216:217], v97, off offset:12
	v_pk_mul_f32 v[90:91], v[90:91], v[156:157]
	v_pk_mul_f32 v[92:93], v[92:93], v[158:159]
	global_atomic_add_f32 v[216:217], v90, off offset:16
	global_atomic_add_f32 v[216:217], v91, off offset:20
	global_atomic_add_f32 v[216:217], v92, off offset:24
	global_atomic_add_f32 v[216:217], v93, off offset:28
	v_pk_mul_f32 v[86:87], v[86:87], v[160:161]
	v_pk_mul_f32 v[88:89], v[88:89], v[162:163]
	global_atomic_add_f32 v[216:217], v86, off offset:512
	global_atomic_add_f32 v[216:217], v87, off offset:516
	global_atomic_add_f32 v[216:217], v88, off offset:520
	global_atomic_add_f32 v[216:217], v89, off offset:524
	v_pk_mul_f32 v[82:83], v[82:83], v[164:165]
	v_pk_mul_f32 v[84:85], v[84:85], v[166:167]
	global_atomic_add_f32 v[216:217], v82, off offset:528
	global_atomic_add_f32 v[216:217], v83, off offset:532
	global_atomic_add_f32 v[216:217], v84, off offset:536
	global_atomic_add_f32 v[216:217], v85, off offset:540
	s_mov_b32 s24, 0x30000
	v_lshl_add_u64 v[218:219], v[146:147], 0, s[24:25]
	v_pk_mul_f32 v[78:79], v[78:79], v[130:131]
	v_pk_mul_f32 v[80:81], v[80:81], v[132:133]
	global_atomic_add_f32 v[218:219], v78, off
	global_atomic_add_f32 v[218:219], v79, off offset:4
	global_atomic_add_f32 v[218:219], v80, off offset:8
	global_atomic_add_f32 v[218:219], v81, off offset:12
	v_pk_mul_f32 v[74:75], v[74:75], v[156:157]
	v_pk_mul_f32 v[76:77], v[76:77], v[158:159]
	global_atomic_add_f32 v[218:219], v74, off offset:16
	global_atomic_add_f32 v[218:219], v75, off offset:20
	global_atomic_add_f32 v[218:219], v76, off offset:24
	global_atomic_add_f32 v[218:219], v77, off offset:28
	v_pk_mul_f32 v[70:71], v[70:71], v[160:161]
	v_pk_mul_f32 v[72:73], v[72:73], v[162:163]
	global_atomic_add_f32 v[218:219], v70, off offset:512
	global_atomic_add_f32 v[218:219], v71, off offset:516
	global_atomic_add_f32 v[218:219], v72, off offset:520
	global_atomic_add_f32 v[218:219], v73, off offset:524
	v_pk_mul_f32 v[66:67], v[66:67], v[164:165]
	v_pk_mul_f32 v[68:69], v[68:69], v[166:167]
	global_atomic_add_f32 v[218:219], v66, off offset:528
	global_atomic_add_f32 v[218:219], v67, off offset:532
	global_atomic_add_f32 v[218:219], v68, off offset:536
	global_atomic_add_f32 v[218:219], v69, off offset:540
	s_mov_b32 s24, 0x80000
	v_lshl_add_u64 v[216:217], v[146:147], 0, s[24:25]
	v_pk_mul_f32 v[62:63], v[62:63], v[130:131]
	v_pk_mul_f32 v[64:65], v[64:65], v[132:133]
	global_atomic_add_f32 v[216:217], v62, off
	global_atomic_add_f32 v[216:217], v63, off offset:4
	global_atomic_add_f32 v[216:217], v64, off offset:8
	global_atomic_add_f32 v[216:217], v65, off offset:12
	v_pk_mul_f32 v[58:59], v[58:59], v[156:157]
	v_pk_mul_f32 v[60:61], v[60:61], v[158:159]
	global_atomic_add_f32 v[216:217], v58, off offset:16
	global_atomic_add_f32 v[216:217], v59, off offset:20
	global_atomic_add_f32 v[216:217], v60, off offset:24
	global_atomic_add_f32 v[216:217], v61, off offset:28
	v_pk_mul_f32 v[54:55], v[54:55], v[160:161]
	v_pk_mul_f32 v[56:57], v[56:57], v[162:163]
	global_atomic_add_f32 v[216:217], v54, off offset:512
	global_atomic_add_f32 v[216:217], v55, off offset:516
	global_atomic_add_f32 v[216:217], v56, off offset:520
	global_atomic_add_f32 v[216:217], v57, off offset:524
	v_pk_mul_f32 v[50:51], v[50:51], v[164:165]
	v_pk_mul_f32 v[52:53], v[52:53], v[166:167]
	global_atomic_add_f32 v[216:217], v50, off offset:528
	global_atomic_add_f32 v[216:217], v51, off offset:532
	global_atomic_add_f32 v[216:217], v52, off offset:536
	global_atomic_add_f32 v[216:217], v53, off offset:540
	s_mov_b32 s24, 0x90000
	v_lshl_add_u64 v[218:219], v[146:147], 0, s[24:25]
	v_pk_mul_f32 v[46:47], v[46:47], v[130:131]
	v_pk_mul_f32 v[48:49], v[48:49], v[132:133]
	global_atomic_add_f32 v[218:219], v46, off
	global_atomic_add_f32 v[218:219], v47, off offset:4
	global_atomic_add_f32 v[218:219], v48, off offset:8
	global_atomic_add_f32 v[218:219], v49, off offset:12
	v_pk_mul_f32 v[42:43], v[42:43], v[156:157]
	v_pk_mul_f32 v[44:45], v[44:45], v[158:159]
	global_atomic_add_f32 v[218:219], v42, off offset:16
	global_atomic_add_f32 v[218:219], v43, off offset:20
	global_atomic_add_f32 v[218:219], v44, off offset:24
	global_atomic_add_f32 v[218:219], v45, off offset:28
	v_pk_mul_f32 v[38:39], v[38:39], v[160:161]
	v_pk_mul_f32 v[40:41], v[40:41], v[162:163]
	global_atomic_add_f32 v[218:219], v38, off offset:512
	global_atomic_add_f32 v[218:219], v39, off offset:516
	global_atomic_add_f32 v[218:219], v40, off offset:520
	global_atomic_add_f32 v[218:219], v41, off offset:524
	v_pk_mul_f32 v[34:35], v[34:35], v[164:165]
	v_pk_mul_f32 v[36:37], v[36:37], v[166:167]
	global_atomic_add_f32 v[218:219], v34, off offset:528
	global_atomic_add_f32 v[218:219], v35, off offset:532
	global_atomic_add_f32 v[218:219], v36, off offset:536
	global_atomic_add_f32 v[218:219], v37, off offset:540
	s_mov_b32 s24, 0xa0000
	v_lshl_add_u64 v[216:217], v[146:147], 0, s[24:25]
	v_pk_mul_f32 v[30:31], v[30:31], v[130:131]
	v_pk_mul_f32 v[32:33], v[32:33], v[132:133]
	global_atomic_add_f32 v[216:217], v30, off
	global_atomic_add_f32 v[216:217], v31, off offset:4
	global_atomic_add_f32 v[216:217], v32, off offset:8
	global_atomic_add_f32 v[216:217], v33, off offset:12
	v_pk_mul_f32 v[26:27], v[26:27], v[156:157]
	v_pk_mul_f32 v[28:29], v[28:29], v[158:159]
	global_atomic_add_f32 v[216:217], v26, off offset:16
	global_atomic_add_f32 v[216:217], v27, off offset:20
	global_atomic_add_f32 v[216:217], v28, off offset:24
	global_atomic_add_f32 v[216:217], v29, off offset:28
	v_pk_mul_f32 v[22:23], v[22:23], v[160:161]
	v_pk_mul_f32 v[24:25], v[24:25], v[162:163]
	global_atomic_add_f32 v[216:217], v22, off offset:512
	global_atomic_add_f32 v[216:217], v23, off offset:516
	global_atomic_add_f32 v[216:217], v24, off offset:520
	global_atomic_add_f32 v[216:217], v25, off offset:524
	v_pk_mul_f32 v[18:19], v[18:19], v[164:165]
	v_pk_mul_f32 v[20:21], v[20:21], v[166:167]
	global_atomic_add_f32 v[216:217], v18, off offset:528
	global_atomic_add_f32 v[216:217], v19, off offset:532
	global_atomic_add_f32 v[216:217], v20, off offset:536
	global_atomic_add_f32 v[216:217], v21, off offset:540
	s_mov_b32 s24, 0xb0000
	v_lshl_add_u64 v[218:219], v[146:147], 0, s[24:25]
	v_pk_mul_f32 v[14:15], v[14:15], v[130:131]
	v_pk_mul_f32 v[16:17], v[16:17], v[132:133]
	global_atomic_add_f32 v[218:219], v14, off
	global_atomic_add_f32 v[218:219], v15, off offset:4
	global_atomic_add_f32 v[218:219], v16, off offset:8
	global_atomic_add_f32 v[218:219], v17, off offset:12
	v_pk_mul_f32 v[10:11], v[10:11], v[156:157]
	v_pk_mul_f32 v[12:13], v[12:13], v[158:159]
	global_atomic_add_f32 v[218:219], v10, off offset:16
	global_atomic_add_f32 v[218:219], v11, off offset:20
	global_atomic_add_f32 v[218:219], v12, off offset:24
	global_atomic_add_f32 v[218:219], v13, off offset:28
	v_pk_mul_f32 v[6:7], v[6:7], v[160:161]
	v_pk_mul_f32 v[8:9], v[8:9], v[162:163]
	global_atomic_add_f32 v[218:219], v6, off offset:512
	global_atomic_add_f32 v[218:219], v7, off offset:516
	global_atomic_add_f32 v[218:219], v8, off offset:520
	global_atomic_add_f32 v[218:219], v9, off offset:524
	v_pk_mul_f32 v[2:3], v[2:3], v[164:165]
	v_pk_mul_f32 v[4:5], v[4:5], v[166:167]
	global_atomic_add_f32 v[218:219], v2, off offset:528
	global_atomic_add_f32 v[218:219], v3, off offset:532
	global_atomic_add_f32 v[218:219], v4, off offset:536
	global_atomic_add_f32 v[218:219], v5, off offset:540
	s_mov_b64 s[40:41], exec
	s_movk_i32 s19, 0x70
	s_branch .LBB0_1865
	global_load_dwordx4 v[156:159], v[146:147], off
	s_waitcnt vmcnt(0)
	v_pk_fma_f32 v[158:159], v[128:129], v[132:133], v[158:159]
	v_pk_fma_f32 v[156:157], v[126:127], v[130:131], v[156:157]
	global_store_dwordx4 v[146:147], v[156:159], off
	s_cbranch_execnz .LBB0_1772
